# adds: GLA next-chunk address set-up moved ahead of the step's first barrier
# speedup vs baseline: 1.0172x; 1.0018x over previous
.LBB0_1317:
	s_waitcnt vmcnt(48)
	v_perm_b32 v26, v115, v115, v32
	v_add_f32_e32 v176, 0, v26
	s_waitcnt vmcnt(45)
	v_perm_b32 v26, v119, v119, v32
	v_add_f32_e32 v177, v176, v26
	s_waitcnt vmcnt(42)
	v_perm_b32 v26, v124, v124, v32
	v_add_f32_e32 v178, v177, v26
	s_waitcnt vmcnt(39)
	v_perm_b32 v26, v132, v132, v32
	v_add_f32_e32 v179, v178, v26
	s_waitcnt vmcnt(36)
	v_perm_b32 v26, v136, v136, v32
	v_add_f32_e32 v180, v179, v26
	s_waitcnt vmcnt(33)
	v_perm_b32 v26, v143, v143, v32
	v_add_f32_e32 v181, v180, v26
	s_waitcnt vmcnt(30)
	v_perm_b32 v26, v146, v146, v32
	v_add_f32_e32 v182, v181, v26
	s_waitcnt vmcnt(27)
	v_perm_b32 v26, v149, v149, v32
	v_add_f32_e32 v183, v182, v26
	s_waitcnt vmcnt(24)
	v_perm_b32 v26, v152, v152, v32
	v_add_f32_e32 v184, v183, v26
	s_waitcnt vmcnt(21)
	v_perm_b32 v26, v155, v155, v32
	v_add_f32_e32 v185, v184, v26
	s_waitcnt vmcnt(18)
	v_perm_b32 v26, v158, v158, v32
	v_add_f32_e32 v186, v185, v26
	s_waitcnt vmcnt(15)
	v_perm_b32 v26, v161, v161, v32
	v_add_f32_e32 v187, v186, v26
	s_waitcnt vmcnt(12)
	v_perm_b32 v26, v164, v164, v32
	v_add_f32_e32 v188, v187, v26
	s_waitcnt vmcnt(9)
	v_perm_b32 v26, v167, v167, v32
	v_add_f32_e32 v189, v188, v26
	s_waitcnt vmcnt(6)
	v_perm_b32 v26, v170, v170, v32
	v_add_f32_e32 v190, v189, v26
	s_waitcnt vmcnt(3)
	v_perm_b32 v26, v173, v173, v32
	v_add_f32_e32 v191, v190, v26
	ds_bpermute_b32 v26, v53, v191
	ds_bpermute_b32 v28, v54, v191
	ds_bpermute_b32 v27, v55, v191
	ds_bpermute_b32 v29, v56, v191
	v_cvt_pk_bf16_f32 v22, v2, v3
	v_cvt_pk_bf16_f32 v23, v4, v5
	v_cvt_pk_bf16_f32 v24, v14, v15
	v_cvt_pk_bf16_f32 v25, v16, v17
	s_add_i32 s78, s74, 0x100
	s_add_i32 s91, s75, 0xffffe000
	v_readfirstlane_b32 s80, v42
	v_readfirstlane_b32 s81, v43
	s_and_b64 s[98:99], s[70:71], exec
	s_cselect_b32 s32, s74, s75
	s_cselect_b32 s78, s78, s91
	s_cselect_b32 s91, 0, 0xffffffd0
	s_cselect_b32 s83, 0, 0xffffffc1
	s_cselect_b32 s99, 0, -1
	s_mov_b32 s98, 0x2000
	s_cselect_b32 s98, s98, 0xffffe000
	s_add_i32 s32, s32, s65
	s_add_i32 s78, s78, s56
	s_cmp_gt_u32 s57, 2
	s_cselect_b32 s32, s32, s78
	s_cmp_eq_u32 s75, -1
	s_cselect_b32 s32, s76, s32
	v_subrev_u32_e32 v204, s91, v139
	v_subrev_u32_e32 v203, s83, v141
	v_lshlrev_b32_e32 v204, 13, v204
	v_lshlrev_b32_e32 v203, 13, v203
	v_subrev_u32_e32 v200, s80, v46
	v_subrev_u32_e32 v201, s80, v44
	v_subrev_u32_e32 v202, s80, v42
	v_add_u32_e32 v203, v203, v48
	v_add_u32_e32 v200, v200, v204
	v_add_u32_e32 v201, v201, v204
	v_add_u32_e32 v202, v202, v204
	v_subrev_u32_e32 v203, s80, v203
	s_add_i32 s78, s32, s91
	s_lshl_b32 s78, s78, 13
	s_add_u32 s80, s80, s78
	s_addc_u32 s81, s81, 0
	s_waitcnt lgkmcnt(0)
	s_barrier
	ds_write2_b64 v103, v[22:23], v[24:25] offset1:4
	v_cvt_pk_bf16_f32 v22, v6, v7
	v_cvt_pk_bf16_f32 v23, v8, v9
	v_cvt_pk_bf16_f32 v24, v10, v11
	v_cvt_pk_bf16_f32 v25, v12, v13
	ds_write2_b64 v103, v[22:23], v[24:25] offset0:8 offset1:12
	v_cndmask_b32_e64 v22, v26, 0, s[0:1]
	v_cndmask_b32_e64 v23, 0, v28, s[2:3]
	v_add_f32_e32 v22, v22, v23
	v_cndmask_b32_e64 v23, 0, v27, s[4:5]
	v_add_f32_e32 v192, v22, v23
	v_pk_add_f32 v[22:23], v[26:27], v[28:29]
	v_add_f32_e32 v22, v22, v23
	v_add_f32_e32 v23, v176, v192
	v_exp_f32_e32 v25, v23
	v_perm_b32 v24, v116, v116, v32
	v_exp_f32_e64 v26, -v23
	v_exp_f32_e32 v22, v22
	v_mul_f32_e32 v23, v25, v24
	v_cvt_pk_bf16_f32 v23, v23, s0
	ds_write_b16 v64, v23
	v_add_f32_e32 v23, v177, v192
	v_exp_f32_e32 v24, v23
	v_exp_f32_e64 v27, -v23
	v_perm_b32 v25, v121, v121, v32
	v_perm_b32 v29, v122, v122, v1
	v_perm_b32 v28, v118, v118, v32
	global_load_dword v115, v200, s[80:81]
	global_load_dword v116, v201, s[80:81]
	global_load_dword v118, v202, s[80:81]
	s_add_u32 s80, s80, s98
	s_addc_u32 s81, s81, s99
	global_load_dword v119, v200, s[80:81]
	global_load_dword v121, v201, s[80:81]
	global_load_dword v122, v202, s[80:81]
	s_add_u32 s80, s80, s98
	s_addc_u32 s81, s81, s99
	v_mul_f32_e32 v23, v24, v25
	v_mul_f32_e32 v24, v26, v28
	v_cvt_pk_bf16_f32 v23, v23, s0
	v_cvt_pk_bf16_f32 v24, v24, s0
	ds_write_b16 v64, v24 offset:17408
	v_pk_mul_f32 v[24:25], v[22:23], v[26:27] op_sel_hi:[0,1]
	ds_write_b16 v65, v23
	v_mul_f32_e32 v23, v27, v29
	v_cvt_pk_bf16_f32 v23, v23, s0
	ds_write_b16 v65, v23 offset:17408
	v_add_f32_e32 v23, v178, v192
	v_pk_mul_f32 v[24:25], v[24:25], v[28:29]
	v_exp_f32_e32 v28, v23
	v_perm_b32 v27, v127, v127, v32
	v_exp_f32_e64 v26, -v23
	v_mul_f32_e32 v23, v28, v27
	v_cvt_pk_bf16_f32 v23, v23, s0
	ds_write_b16 v66, v23
	v_add_f32_e32 v23, v179, v192
	v_exp_f32_e32 v28, v23
	v_perm_b32 v177, v133, v133, v32
	v_exp_f32_e64 v27, -v23
	v_mul_f32_e32 v23, v28, v177
	v_perm_b32 v28, v130, v130, v32
	global_load_dword v124, v200, s[80:81]
	global_load_dword v127, v201, s[80:81]
	global_load_dword v130, v202, s[80:81]
	s_add_u32 s80, s80, s98
	s_addc_u32 s81, s81, s99
	v_mul_f32_e32 v176, v26, v28
	v_cvt_pk_bf16_f32 v23, v23, s0
	v_perm_b32 v29, v135, v135, v1
	global_load_dword v132, v200, s[80:81]
	global_load_dword v133, v201, s[80:81]
	global_load_dword v135, v202, s[80:81]
	s_add_u32 s80, s80, s98
	s_addc_u32 s81, s81, s99
	v_cvt_pk_bf16_f32 v176, v176, s0
	ds_write_b16 v66, v176 offset:17408
	v_pk_mul_f32 v[176:177], v[22:23], v[26:27] op_sel_hi:[0,1]
	ds_write_b16 v67, v23
	v_mul_f32_e32 v23, v27, v29
	v_cvt_pk_bf16_f32 v23, v23, s0
	ds_write_b16 v67, v23 offset:17408
	v_add_f32_e32 v23, v180, v192
	v_pk_mul_f32 v[176:177], v[176:177], v[28:29]
	v_exp_f32_e32 v28, v23
	v_perm_b32 v27, v137, v137, v32
	v_exp_f32_e64 v26, -v23
	v_mul_f32_e32 v23, v28, v27
	v_cvt_pk_bf16_f32 v23, v23, s0
	ds_write_b16 v68, v23
	v_add_f32_e32 v23, v181, v192
	v_exp_f32_e32 v28, v23
	v_perm_b32 v179, v144, v144, v32
	v_exp_f32_e64 v27, -v23
	v_mul_f32_e32 v23, v28, v179
	v_perm_b32 v28, v138, v138, v32
	global_load_dword v136, v200, s[80:81]
	global_load_dword v137, v201, s[80:81]
	global_load_dword v138, v202, s[80:81]
	s_add_u32 s80, s80, s98
	s_addc_u32 s81, s81, s99
	v_mul_f32_e32 v178, v26, v28
	v_cvt_pk_bf16_f32 v23, v23, s0
	v_perm_b32 v29, v145, v145, v1
	global_load_dword v143, v200, s[80:81]
	global_load_dword v144, v201, s[80:81]
	global_load_dword v145, v202, s[80:81]
	s_add_u32 s80, s80, s98
	s_addc_u32 s81, s81, s99
	v_cvt_pk_bf16_f32 v178, v178, s0
	ds_write_b16 v68, v178 offset:17408
	v_pk_mul_f32 v[178:179], v[22:23], v[26:27] op_sel_hi:[0,1]
	ds_write_b16 v69, v23
	v_mul_f32_e32 v23, v27, v29
	v_cvt_pk_bf16_f32 v23, v23, s0
	ds_write_b16 v69, v23 offset:17408
	v_add_f32_e32 v23, v182, v192
	v_pk_mul_f32 v[178:179], v[178:179], v[28:29]
	v_exp_f32_e32 v28, v23
	v_perm_b32 v27, v147, v147, v32
	v_exp_f32_e64 v26, -v23
	v_mul_f32_e32 v23, v28, v27
	v_cvt_pk_bf16_f32 v23, v23, s0
	ds_write_b16 v70, v23
	v_add_f32_e32 v23, v183, v192
	v_exp_f32_e32 v28, v23
	v_perm_b32 v181, v150, v150, v32
	v_exp_f32_e64 v27, -v23
	v_mul_f32_e32 v23, v28, v181
	v_perm_b32 v28, v148, v148, v32
	global_load_dword v146, v200, s[80:81]
	global_load_dword v147, v201, s[80:81]
	global_load_dword v148, v202, s[80:81]
	s_add_u32 s80, s80, s98
	s_addc_u32 s81, s81, s99
	v_mul_f32_e32 v180, v26, v28
	v_cvt_pk_bf16_f32 v23, v23, s0
	v_perm_b32 v29, v151, v151, v1
	global_load_dword v149, v200, s[80:81]
	global_load_dword v150, v201, s[80:81]
	global_load_dword v151, v202, s[80:81]
	s_add_u32 s80, s80, s98
	s_addc_u32 s81, s81, s99
	v_cvt_pk_bf16_f32 v180, v180, s0
	ds_write_b16 v70, v180 offset:17408
	v_pk_mul_f32 v[180:181], v[22:23], v[26:27] op_sel_hi:[0,1]
	ds_write_b16 v71, v23
	v_mul_f32_e32 v23, v27, v29
	v_cvt_pk_bf16_f32 v23, v23, s0
	ds_write_b16 v71, v23 offset:17408
	v_add_f32_e32 v23, v184, v192
	v_pk_mul_f32 v[180:181], v[180:181], v[28:29]
	v_exp_f32_e32 v28, v23
	v_perm_b32 v27, v153, v153, v32
	v_exp_f32_e64 v26, -v23
	v_mul_f32_e32 v23, v28, v27
	v_cvt_pk_bf16_f32 v23, v23, s0
	ds_write_b16 v72, v23
	v_add_f32_e32 v23, v185, v192
	v_exp_f32_e32 v28, v23
	v_perm_b32 v183, v156, v156, v32
	v_exp_f32_e64 v27, -v23
	v_mul_f32_e32 v23, v28, v183
	v_perm_b32 v28, v154, v154, v32
	global_load_dword v152, v200, s[80:81]
	global_load_dword v153, v201, s[80:81]
	global_load_dword v154, v202, s[80:81]
	s_add_u32 s80, s80, s98
	s_addc_u32 s81, s81, s99
	v_mul_f32_e32 v182, v26, v28
	v_cvt_pk_bf16_f32 v23, v23, s0
	v_perm_b32 v29, v157, v157, v1
	global_load_dword v155, v200, s[80:81]
	global_load_dword v156, v201, s[80:81]
	global_load_dword v157, v202, s[80:81]
	s_add_u32 s80, s80, s98
	s_addc_u32 s81, s81, s99
	v_cvt_pk_bf16_f32 v182, v182, s0
	ds_write_b16 v72, v182 offset:17408
	v_pk_mul_f32 v[182:183], v[22:23], v[26:27] op_sel_hi:[0,1]
	ds_write_b16 v73, v23
	v_mul_f32_e32 v23, v27, v29
	v_cvt_pk_bf16_f32 v23, v23, s0
	ds_write_b16 v73, v23 offset:17408
	v_add_f32_e32 v23, v186, v192
	v_pk_mul_f32 v[182:183], v[182:183], v[28:29]
	v_exp_f32_e32 v28, v23
	v_perm_b32 v27, v159, v159, v32
	v_exp_f32_e64 v26, -v23
	v_mul_f32_e32 v23, v28, v27
	v_cvt_pk_bf16_f32 v23, v23, s0
	ds_write_b16 v74, v23
	v_add_f32_e32 v23, v187, v192
	v_exp_f32_e32 v28, v23
	v_perm_b32 v185, v162, v162, v32
	v_exp_f32_e64 v27, -v23
	v_mul_f32_e32 v23, v28, v185
	v_perm_b32 v28, v160, v160, v32
	global_load_dword v158, v200, s[80:81]
	global_load_dword v159, v201, s[80:81]
	global_load_dword v160, v202, s[80:81]
	s_add_u32 s80, s80, s98
	s_addc_u32 s81, s81, s99
	v_mul_f32_e32 v184, v26, v28
	v_cvt_pk_bf16_f32 v23, v23, s0
	v_perm_b32 v29, v163, v163, v1
	global_load_dword v161, v200, s[80:81]
	global_load_dword v162, v201, s[80:81]
	global_load_dword v163, v202, s[80:81]
	s_add_u32 s80, s80, s98
	s_addc_u32 s81, s81, s99
	v_cvt_pk_bf16_f32 v184, v184, s0
	ds_write_b16 v74, v184 offset:17408
	v_pk_mul_f32 v[184:185], v[22:23], v[26:27] op_sel_hi:[0,1]
	ds_write_b16 v75, v23
	v_mul_f32_e32 v23, v27, v29
	v_cvt_pk_bf16_f32 v23, v23, s0
	ds_write_b16 v75, v23 offset:17408
	v_add_f32_e32 v23, v188, v192
	v_pk_mul_f32 v[184:185], v[184:185], v[28:29]
	v_exp_f32_e32 v28, v23
	v_perm_b32 v27, v165, v165, v32
	v_exp_f32_e64 v26, -v23
	v_mul_f32_e32 v23, v28, v27
	v_cvt_pk_bf16_f32 v23, v23, s0
	ds_write_b16 v76, v23
	v_add_f32_e32 v23, v189, v192
	v_exp_f32_e32 v28, v23
	v_perm_b32 v187, v168, v168, v32
	v_exp_f32_e64 v27, -v23
	v_mul_f32_e32 v23, v28, v187
	v_perm_b32 v28, v166, v166, v32
	global_load_dword v164, v200, s[80:81]
	global_load_dword v165, v201, s[80:81]
	global_load_dword v166, v202, s[80:81]
	s_add_u32 s80, s80, s98
	s_addc_u32 s81, s81, s99
	v_mul_f32_e32 v186, v26, v28
	v_cvt_pk_bf16_f32 v23, v23, s0
	v_perm_b32 v29, v169, v169, v1
	global_load_dword v167, v200, s[80:81]
	global_load_dword v168, v201, s[80:81]
	global_load_dword v169, v202, s[80:81]
	s_add_u32 s80, s80, s98
	s_addc_u32 s81, s81, s99
	v_cvt_pk_bf16_f32 v186, v186, s0
	ds_write_b16 v76, v186 offset:17408
	v_pk_mul_f32 v[186:187], v[22:23], v[26:27] op_sel_hi:[0,1]
	ds_write_b16 v77, v23
	v_mul_f32_e32 v23, v27, v29
	v_cvt_pk_bf16_f32 v23, v23, s0
	ds_write_b16 v77, v23 offset:17408
	v_add_f32_e32 v23, v190, v192
	v_exp_f32_e32 v27, v23
	v_perm_b32 v26, v171, v171, v32
	v_pk_mul_f32 v[186:187], v[186:187], v[28:29]
	v_exp_f32_e64 v28, -v23
	v_mul_f32_e32 v23, v27, v26
	v_cvt_pk_bf16_f32 v23, v23, s0
	ds_write_b16 v78, v23
	v_add_f32_e32 v23, v191, v192
	v_exp_f32_e32 v26, v23
	s_waitcnt vmcnt(43)
	v_exp_f32_e64 v29, -v23
	v_perm_b32 v27, v174, v174, v32
	v_perm_b32 v189, v175, v175, v1
	v_perm_b32 v188, v172, v172, v32
	global_load_dword v170, v200, s[80:81]
	global_load_dword v171, v201, s[80:81]
	global_load_dword v172, v202, s[80:81]
	s_add_u32 s80, s80, s98
	s_addc_u32 s81, s81, s99
	global_load_dword v173, v200, s[80:81]
	global_load_dword v174, v201, s[80:81]
	global_load_dword v175, v202, s[80:81]
	v_mul_f32_e32 v23, v26, v27
	v_mul_f32_e32 v26, v28, v188
	v_cvt_pk_bf16_f32 v23, v23, s0
	v_cvt_pk_bf16_f32 v26, v26, s0
	ds_write_b16 v78, v26 offset:17408
	ds_write_b16 v79, v23
	v_mul_f32_e32 v23, v29, v189
	v_cvt_pk_bf16_f32 v23, v23, s0
	v_pk_mul_f32 v[28:29], v[22:23], v[28:29] op_sel_hi:[0,1]
	v_cvt_pk_bf16_f32 v24, v24, v25
	v_cvt_pk_bf16_f32 v25, v176, v177
	v_cvt_pk_bf16_f32 v26, v178, v179
	v_cvt_pk_bf16_f32 v27, v180, v181
	v_pk_mul_f32 v[28:29], v[28:29], v[188:189]
	ds_write_b16 v79, v23 offset:17408
	v_cvt_pk_bf16_f32 v176, v182, v183
	v_cvt_pk_bf16_f32 v177, v184, v185
	v_cvt_pk_bf16_f32 v178, v186, v187
	v_cvt_pk_bf16_f32 v179, v28, v29
	ds_write_b128 v57, v[24:27] offset:34816
	ds_write_b128 v57, v[176:179] offset:34832
	s_and_saveexec_b64 s[72:73], s[0:1]
	ds_write_b32 v61, v22
	s_or_b64 exec, exec, s[72:73]
	s_cmp_eq_u32 s75, -1
	s_mov_b32 s10, s76
	s_waitcnt vmcnt(48)
	ds_write_b16 v58, v18 offset:53248
	ds_write_b16_d16_hi v58, v18 offset:53392
	ds_write_b16 v58, v19 offset:53536
	ds_write_b16_d16_hi v58, v19 offset:53680
	ds_write_b16 v58, v20 offset:53824
	ds_write_b16_d16_hi v58, v20 offset:53968
	ds_write_b16 v58, v21 offset:54112
	ds_write_b16_d16_hi v59, v21 offset:53248
	s_cbranch_scc1 .LBB0_1325
	s_cmp_gt_u32 s57, 2
	s_mov_b64 s[72:73], -1
	s_cbranch_scc0 .LBB0_1322
	s_and_b64 s[10:11], s[70:71], exec
	s_cselect_b32 s10, s74, s75
	s_add_i32 s10, s10, s65
	s_mov_b64 s[72:73], 0
